# attention pp4 loop: last P.V key step (4 MFMAs) moved from the QK^T segment back to the P.V segment (16+16 instead of 12+20); on top of v2
# baseline (speedup 1.0000x reference)
.LBB0_753:
	s_lshl_b32 s43, s13, 14
	v_add_u32_e32 v142, s43, v159
	v_add_u32_e32 v143, s43, v160
	v_add_u32_e32 v144, s43, v161
	v_add_u32_e32 v154, s43, v162
	ds_read_b128 v[164:167], v142 offset:0
	ds_read_b128 v[168:171], v143 offset:0
	ds_read_b128 v[172:175], v144 offset:0
	ds_read_b128 v[130:133], v154 offset:0
	ds_read_b128 v[176:179], v142 offset:0x1000
	ds_read_b128 v[180:183], v143 offset:0x1000
	ds_read_b128 v[184:187], v144 offset:0x1000
	ds_read_b128 v[134:137], v154 offset:0x1000
	ds_read_b128 v[188:191], v142 offset:0x2000
	ds_read_b128 v[192:195], v143 offset:0x2000
	ds_read_b128 v[196:199], v144 offset:0x2000
	ds_read_b128 v[138:141], v154 offset:0x2000
	ds_read_b128 v[200:203], v142 offset:0x3000
	ds_read_b128 v[204:207], v143 offset:0x3000
	ds_read_b128 v[208:211], v144 offset:0x3000
	ds_read_b128 v[142:145], v154 offset:0x3000
	v_exp_f32_e32 v90, v90
	v_exp_f32_e32 v212, v91
	v_exp_f32_e32 v91, v92
	v_exp_f32_e32 v213, v93
	v_exp_f32_e32 v92, v94
	v_exp_f32_e32 v94, v95
	v_exp_f32_e32 v93, v96
	v_exp_f32_e32 v95, v97
	v_exp_f32_e32 v82, v82
	v_exp_f32_e32 v83, v83
	v_exp_f32_e32 v84, v84
	v_exp_f32_e32 v85, v85
	v_pk_add_f32 v[96:97], v[90:91], v[212:213]
	v_pk_add_f32 v[214:215], v[92:93], v[94:95]
	v_pk_add_f32 v[96:97], v[96:97], v[96:97] op_sel_hi:[0,1]
	v_cvt_pk_bf16_f32 v90, v90, v212
	v_cvt_pk_bf16_f32 v91, v91, v213
	v_cvt_pk_bf16_f32 v92, v92, v94
	v_exp_f32_e32 v86, v86
	v_exp_f32_e32 v94, v87
	v_exp_f32_e32 v88, v88
	v_exp_f32_e32 v96, v89
	v_cvt_pk_bf16_f32 v93, v93, v95
	v_add_f32_e32 v87, v82, v83
	v_add_f32_e32 v89, v84, v85
	v_cvt_pk_bf16_f32 v82, v82, v83
	v_cvt_pk_bf16_f32 v83, v84, v85
	v_cvt_pk_bf16_f32 v84, v86, v94
	v_cvt_pk_bf16_f32 v85, v88, v96
	s_waitcnt lgkmcnt(0)
	s_barrier
	v_permlane32_swap_b32_e32 v90, v92
	v_permlane32_swap_b32_e32 v91, v93
	v_add_f32_e32 v95, v86, v94
	v_permlane32_swap_b32_e32 v82, v84
	v_permlane32_swap_b32_e32 v83, v85
	v_pk_add_f32 v[214:215], v[214:215], v[214:215] op_sel_hi:[0,1]
	v_add_f32_e32 v213, v88, v96
	s_setprio 0
	v_mfma_f32_32x32x16_bf16 v[50:65], v[82:85], v[164:167], v[50:65]
	v_mfma_f32_32x32x16_bf16 v[34:49], v[82:85], v[176:179], v[34:49]
	v_mfma_f32_32x32x16_bf16 v[18:33], v[82:85], v[188:191], v[18:33]
	v_mfma_f32_32x32x16_bf16 v[2:17], v[82:85], v[200:203], v[2:17]
	v_exp_f32_e32 v86, v66
	v_exp_f32_e32 v88, v67
	v_exp_f32_e32 v94, v68
	v_exp_f32_e32 v212, v69
	v_mfma_f32_32x32x16_bf16 v[50:65], v[90:93], v[168:171], v[50:65]
	v_exp_f32_e32 v82, v70
	v_exp_f32_e32 v83, v71
	v_exp_f32_e32 v96, v72
	v_exp_f32_e32 v214, v73
	v_pk_add_f32 v[66:67], v[86:87], v[88:89]
	v_pk_add_f32 v[68:69], v[94:95], v[212:213]
	v_add_f32_e32 v154, v82, v83
	v_mfma_f32_32x32x16_bf16 v[34:49], v[90:93], v[180:183], v[34:49]
	v_add_f32_e64 v66, v66, v68
	v_add_f32_e64 v67, v67, v69
	v_add_f32_e64 v68, v96, v214
	v_add_f32_e64 v69, v97, v215
	v_add_f32_e64 v68, v154, v68
	v_add_f32_e64 v69, v155, v69
	v_pk_add_f32 v[70:71], v[66:67], v[68:69]
	v_cvt_pk_bf16_f32 v66, v86, v88
	v_mfma_f32_32x32x16_bf16 v[18:33], v[90:93], v[192:195], v[18:33]
	v_cvt_pk_bf16_f32 v67, v94, v212
	v_cvt_pk_bf16_f32 v68, v82, v83
	v_cvt_pk_bf16_f32 v69, v96, v214
	s_nop 0
	v_permlane32_swap_b32_e32 v66, v68
	v_permlane32_swap_b32_e32 v67, v69
	v_mfma_f32_32x32x16_bf16 v[2:17], v[90:93], v[204:207], v[2:17]
	v_exp_f32_e32 v72, v74
	v_exp_f32_e32 v74, v75
	v_mfma_f32_32x32x16_bf16 v[50:65], v[66:69], v[172:175], v[50:65]
	v_exp_f32_e32 v76, v76
	v_exp_f32_e32 v82, v77
	v_exp_f32_e32 v73, v78
	v_exp_f32_e32 v75, v79
	v_exp_f32_e32 v77, v80
	v_exp_f32_e32 v83, v81
	v_add_f32_e32 v70, v70, v71
	v_mfma_f32_32x32x16_bf16 v[34:49], v[66:69], v[184:187], v[34:49]
	v_add_f32_e64 v78, v72, v74
	v_add_f32_e64 v79, v73, v75
	v_add_f32_e64 v80, v76, v82
	v_add_f32_e64 v81, v77, v83
	v_cvt_pk_bf16_f32 v164, v72, v74
	v_cvt_pk_bf16_f32 v165, v76, v82
	v_cvt_pk_bf16_f32 v166, v73, v75
	v_cvt_pk_bf16_f32 v167, v77, v83
	v_mfma_f32_32x32x16_bf16 v[18:33], v[66:69], v[196:199], v[18:33]
	v_add_f32_e64 v78, v78, v80
	v_add_f32_e64 v79, v79, v81
	v_permlane32_swap_b32_e32 v164, v166
	v_add_f32_e32 v71, v78, v79
	v_add_f32_e32 v155, v71, v70
	v_permlane32_swap_b32_e32 v165, v167
	v_mfma_f32_32x32x16_bf16 v[2:17], v[66:69], v[208:211], v[2:17]
	s_nop 1
	v_mfma_f32_32x32x16_bf16 v[50:65], v[164:167], v[130:133], v[50:65]
	v_mfma_f32_32x32x16_bf16 v[34:49], v[164:167], v[134:137], v[34:49]
	v_mfma_f32_32x32x16_bf16 v[18:33], v[164:167], v[138:141], v[18:33]
	v_mfma_f32_32x32x16_bf16 v[2:17], v[164:167], v[142:145], v[2:17]
	s_setprio 0
	s_waitcnt lgkmcnt(0)
	s_barrier
	v_mov_b32_e32 v74, v163
	v_lshl_add_u32 v75, s9, 14, v158
	s_nop 0
	v_add_u32_e32 v76, v74, v75
	ds_read_b128 v[66:69], v76 offset:0
	ds_read_b128 v[70:73], v76 offset:0x2000
	v_xad_u32 v77, v74, 32, v75
	ds_read_b128 v[168:171], v77 offset:0
	ds_read_b128 v[172:175], v77 offset:0x2000
	v_xad_u32 v76, v74, 64, v75
	ds_read_b128 v[176:179], v76 offset:0
	ds_read_b128 v[180:183], v76 offset:0x2000
	v_xad_u32 v77, v74, s66, v75
	ds_read_b128 v[184:187], v77 offset:0
	ds_read_b128 v[188:191], v77 offset:0x2000
	v_xad_u32 v76, v74, s67, v75
	ds_read_b128 v[192:195], v76 offset:0
	ds_read_b128 v[196:199], v76 offset:0x2000
	v_xad_u32 v77, v74, s68, v75
	ds_read_b128 v[200:203], v77 offset:0
	ds_read_b128 v[204:207], v77 offset:0x2000
	v_xad_u32 v76, v74, s69, v75
	ds_read_b128 v[208:211], v76 offset:0
	ds_read_b128 v[212:215], v76 offset:0x2000
	v_xad_u32 v74, v74, s74, v75
	ds_read_b128 v[216:219], v74 offset:0
	ds_read_b128 v[220:223], v74 offset:0x2000
	s_add_i32 s43, s42, 3
	s_min_i32 s44, s43, s22
	s_add_i32 s43, s42, 2
	s_min_i32 s46, s43, s22
	s_ashr_i32 s45, s44, 31
	s_lshl_b32 s43, s23, 14
	s_lshl_b64 s[44:45], s[44:45], 14
	s_add_i32 s43, s8, s43
	s_waitcnt vmcnt(0)
	v_lshl_add_u64 v[74:75], v[146:147], 0, s[44:45]
	s_mov_b32 m0, s43
	s_ashr_i32 s47, s46, 31
	global_load_lds_dwordx4 v[74:75], off
	s_add_i32 m0, s43, 0x2000
	s_lshl_b32 s43, s12, 14
	v_lshl_add_u64 v[74:75], v[148:149], 0, s[44:45]
	s_lshl_b64 s[44:45], s[46:47], 14
	s_add_i32 s43, s8, s43
	global_load_lds_dwordx4 v[74:75], off
	v_lshl_add_u64 v[74:75], v[150:151], 0, s[44:45]
	s_add_i32 m0, s43, 0xc000
	s_nop 0
	global_load_lds_dwordx4 v[74:75], off
	v_lshl_add_u64 v[74:75], v[152:153], 0, s[44:45]
	s_add_i32 m0, s43, 0xe000
	s_nop 0
	global_load_lds_dwordx4 v[74:75], off
	s_waitcnt lgkmcnt(0)
	s_barrier
	s_setprio 0
	v_mfma_f32_32x32x16_bf16 v[82:97], v[66:69], v[98:101], 0
	v_mfma_f32_32x32x16_bf16 v[66:81], v[70:73], v[98:101], 0
	v_mfma_f32_32x32x16_bf16 v[82:97], v[168:171], v[102:105], v[82:97]
	v_mfma_f32_32x32x16_bf16 v[66:81], v[172:175], v[102:105], v[66:81]
	v_mfma_f32_32x32x16_bf16 v[82:97], v[176:179], v[106:109], v[82:97]
	v_mfma_f32_32x32x16_bf16 v[66:81], v[180:183], v[106:109], v[66:81]
	v_mfma_f32_32x32x16_bf16 v[82:97], v[184:187], v[110:113], v[82:97]
	v_mfma_f32_32x32x16_bf16 v[66:81], v[188:191], v[110:113], v[66:81]
	v_mfma_f32_32x32x16_bf16 v[82:97], v[192:195], v[114:117], v[82:97]
	v_mfma_f32_32x32x16_bf16 v[66:81], v[196:199], v[114:117], v[66:81]
	v_mfma_f32_32x32x16_bf16 v[82:97], v[200:203], v[118:121], v[82:97]
	v_mfma_f32_32x32x16_bf16 v[66:81], v[204:207], v[118:121], v[66:81]
	v_mfma_f32_32x32x16_bf16 v[82:97], v[208:211], v[122:125], v[82:97]
	v_mfma_f32_32x32x16_bf16 v[66:81], v[212:215], v[122:125], v[66:81]
	v_mfma_f32_32x32x16_bf16 v[82:97], v[216:219], v[126:129], v[82:97]
	v_mfma_f32_32x32x16_bf16 v[66:81], v[220:223], v[126:129], v[66:81]
	s_setprio 0
	s_add_i32 s43, s9, 1
	s_cmp_lg_u32 s9, 2
	s_cselect_b32 s9, s43, 0
	s_add_i32 s43, s13, 1
	s_cmp_lg_u32 s13, 2
	s_cselect_b32 s13, s43, 0
	s_add_i32 s43, s23, 1
	s_cmp_lg_u32 s23, 2
	s_cselect_b32 s23, s43, 0
	s_add_i32 s43, s12, 1
	s_waitcnt lgkmcnt(0)
	s_barrier
	s_cmp_lg_u32 s12, 2
	s_cselect_b32 s12, s43, 0
	s_add_i32 s42, s42, 1
	s_cmp_eq_u32 s21, s42
	s_cbranch_scc0 .LBB0_753
	s_setprio 0
	s_and_b64 vcc, exec, s[28:29]
	s_cbranch_vccz .LBB0_756
	s_waitcnt lgkmcnt(0)
	s_barrier
